# DA fast path: per-cluster s_setprio (1 around QK/PV MFMA clusters, 0 in softmax) on top of v19
# speedup vs baseline: 1.0177x; 1.0102x over previous
; template <int NC, int DQK, int DV, bool CAUSAL, bool PF> ...
;     ...
;     _Pragma("unroll") for (int c = 0; c < NC; ++c) {
;       f32x4 s[4];
;       _Pragma("unroll") for (int m = 0; m < 4; ++m) s[m] = f32x4{0.f, 0.f, 0.f, 0.f};
;       _Pragma("unroll") for (int ks = 0; ks < NKS; ++ks) _Pragma("unroll") for (int m = 0; m < 4; ++m) {
;         bf16x8 a = *(const bf16x8*)&Kb[(16 * m + fr) * KLD + c * DQK + ks * 32 + fq * 8];
;         s[m] = __builtin_amdgcn_mfma_f32_16x16x32_bf16(a, qf[c][ks], s[m], 0, 0, 0);
;       }
;       constexpr float THR = 8.f;
;       float tnew, psum = 0.f;
;       if (general) {
;         float tmax = -1e30f;
;         _Pragma("unroll") for (int m = 0; m < 4; ++m) _Pragma("unroll") for (int j = 0; j < 4; ++j) {
;           float v = s[m][j] * scale_log2 + bv[m][j];
;           s[m][j] = v; tmax = fmaxf(tmax, v);
;         }
;         tnew = tmax;
;       } else {
;         float rmax = fmaxf(fmaxf(s[0][0], s[0][1]), fmaxf(s[0][2], s[0][3]));
;         _Pragma("unroll") for (int m = 1; m < 4; ++m) rmax = fmaxf(rmax, fmaxf(fmaxf(s[m][0], s[m][1]), fmaxf(s[m][2], s[m][3])));
;         tnew = rmax * scale_log2 + bb;
;       }
;       if (__builtin_amdgcn_ballot_w64(tnew - mrun[c] > THR) != 0ull) {
.Lda_fast:
	s_setprio 1
	v_add3_u32 v172, s38, v32, v195
	v_add3_u32 v173, s37, v32, v193
	ds_read_b128 v[146:149], v172
	ds_read_b128 v[150:153], v172 offset:4608
	ds_read_b128 v[154:157], v172 offset:9216
	ds_read_b128 v[158:161], v172 offset:13824
	ds_read_b128 v[16:19], v172 offset:64
	ds_read_b128 v[20:23], v172 offset:4672
	ds_read_b128 v[24:27], v172 offset:9280
	ds_read_b128 v[28:31], v172 offset:13888
	ds_read_b128 v[0:3], v172 offset:128
	ds_read_b128 v[4:7], v172 offset:4736
	ds_read_b128 v[8:11], v172 offset:9344
	ds_read_b128 v[12:15], v172 offset:13952
	s_waitcnt lgkmcnt(10)
	v_mfma_f32_16x16x32_bf16 v[146:149], v[146:149], v[138:141], 0
	v_mfma_f32_16x16x32_bf16 v[150:153], v[150:153], v[138:141], 0
	s_waitcnt lgkmcnt(8)
	v_mfma_f32_16x16x32_bf16 v[154:157], v[154:157], v[138:141], 0
	v_mfma_f32_16x16x32_bf16 v[158:161], v[158:161], v[138:141], 0
	s_waitcnt lgkmcnt(4)
	v_mfma_f32_16x16x32_bf16 v[146:149], v[16:19], v[134:137], v[146:149]
	v_mfma_f32_16x16x32_bf16 v[150:153], v[20:23], v[134:137], v[150:153]
	v_mfma_f32_16x16x32_bf16 v[154:157], v[24:27], v[134:137], v[154:157]
	v_mfma_f32_16x16x32_bf16 v[158:161], v[28:31], v[134:137], v[158:161]
	ds_read_b128 v[16:19], v172 offset:192
	ds_read_b128 v[20:23], v172 offset:4800
	ds_read_b128 v[24:27], v172 offset:9408
	ds_read_b128 v[28:31], v172 offset:14016
	ds_read_b128 v[122:125], v173 offset:36864
	ds_read_b128 v[126:129], v173 offset:39424
	ds_read_b128 v[130:133], v173 offset:41984
	ds_read_b128 v[142:145], v173 offset:44544
	s_waitcnt lgkmcnt(8)
	v_mfma_f32_16x16x32_bf16 v[0:3], v[0:3], v[118:121], 0
	v_mfma_f32_16x16x32_bf16 v[4:7], v[4:7], v[118:121], 0
	v_mfma_f32_16x16x32_bf16 v[8:11], v[8:11], v[118:121], 0
	v_mfma_f32_16x16x32_bf16 v[12:15], v[12:15], v[118:121], 0
	s_setprio 0
	v_max3_f32 v174, v146, v147, v148
	v_max3_f32 v175, v149, v150, v151
	v_max3_f32 v174, v174, v152, v153
	v_max3_f32 v175, v175, v154, v155
	v_max3_f32 v174, v174, v156, v157
	v_max3_f32 v175, v175, v158, v159
	v_max3_f32 v174, v174, v160, v161
	v_max_f32_e32 v174, v174, v175
	v_fmamk_f32 v174, v174, 0x3e38aa3b, v170
	v_sub_f32_e32 v175, v174, v194
	v_cmp_lt_f32_e32 vcc, s33, v175
	s_cbranch_vccnz .Lda_resc0

; __device__ __forceinline__ uint2 pack4(float a, float b, float c, float d) { uint2 r; r.x = pk2(a, b); r.y = pk2(c, d); return r; }
; template <int NC, int DQK, int DV, bool CAUSAL, bool PF> ...
;     ...
;         float cc = bb - mrun[c];
;         _Pragma("unroll") for (int m = 0; m < 4; ++m) _Pragma("unroll") for (int j = 0; j < 4; ++j) { float pv = __builtin_amdgcn_exp2f(s[m][j] * scale_log2 + cc); s[m][j] = pv; psum += pv; }
;       }
;       lsum[c] += psum;
;       _Pragma("unroll") for (int k2 = 0; k2 < 2; ++k2) {
;         uint2 lo = pack4(s[2 * k2][0], s[2 * k2][1], s[2 * k2][2], s[2 * k2][3]);
;         uint2 hi = pack4(s[2 * k2 + 1][0], s[2 * k2 + 1][1], s[2 * k2 + 1][2], s[2 * k2 + 1][3]);
;         uint4 pk; pk.x = lo.x; pk.y = lo.y; pk.z = hi.x; pk.w = hi.y;
;         pf[c][k2] = *(bf16x8*)&pk;
;       }
;     }
;     _Pragma("unroll") for (int k2 = 0; k2 < 2; ++k2) _Pragma("unroll") for (int v = 0; v < NVT; ++v) {
;       bf16x8 a = *(const bf16x8*)&Vb[(16 * v + fr) * VLD + 32 * k2 + fq * 8];
;       _Pragma("unroll") for (int c = 0; c < NC; ++c) O[c][v] = __builtin_amdgcn_mfma_f32_16x16x32_bf16(a, pf[c][k2], O[c][v], 0, 0, 0);
;       if ((v & 3) == 3) __builtin_amdgcn_sched_barrier(0);
;     }
.Lda_resc1_ret:
	v_sub_f32_e32 v175, v170, v171
	v_fmamk_f32 v0, v0, 0x3e38aa3b, v175
	v_fmamk_f32 v1, v1, 0x3e38aa3b, v175
	v_fmamk_f32 v2, v2, 0x3e38aa3b, v175
	v_fmamk_f32 v3, v3, 0x3e38aa3b, v175
	v_fmamk_f32 v4, v4, 0x3e38aa3b, v175
	v_fmamk_f32 v5, v5, 0x3e38aa3b, v175
	v_fmamk_f32 v6, v6, 0x3e38aa3b, v175
	v_fmamk_f32 v7, v7, 0x3e38aa3b, v175
	v_fmamk_f32 v8, v8, 0x3e38aa3b, v175
	v_fmamk_f32 v9, v9, 0x3e38aa3b, v175
	v_fmamk_f32 v10, v10, 0x3e38aa3b, v175
	v_fmamk_f32 v11, v11, 0x3e38aa3b, v175
	v_fmamk_f32 v12, v12, 0x3e38aa3b, v175
	v_fmamk_f32 v13, v13, 0x3e38aa3b, v175
	v_fmamk_f32 v14, v14, 0x3e38aa3b, v175
	v_fmamk_f32 v15, v15, 0x3e38aa3b, v175
	v_exp_f32_e32 v0, v0
	v_exp_f32_e32 v1, v1
	v_exp_f32_e32 v2, v2
	v_add_f32_e32 v174, v1, v0
	v_exp_f32_e32 v3, v3
	v_add_f32_e32 v174, v2, v174
	v_exp_f32_e32 v4, v4
	v_add_f32_e32 v174, v3, v174
	v_exp_f32_e32 v5, v5
	v_add_f32_e32 v174, v4, v174
	v_exp_f32_e32 v6, v6
	v_add_f32_e32 v174, v5, v174
	v_exp_f32_e32 v7, v7
	v_add_f32_e32 v174, v6, v174
	v_exp_f32_e32 v8, v8
	v_add_f32_e32 v174, v7, v174
	v_exp_f32_e32 v9, v9
	v_add_f32_e32 v174, v8, v174
	v_exp_f32_e32 v10, v10
	v_add_f32_e32 v174, v9, v174
	v_exp_f32_e32 v11, v11
	v_add_f32_e32 v174, v10, v174
	v_exp_f32_e32 v12, v12
	v_add_f32_e32 v174, v11, v174
	v_exp_f32_e32 v13, v13
	v_add_f32_e32 v174, v12, v174
	v_exp_f32_e32 v14, v14
	v_add_f32_e32 v174, v13, v174
	v_exp_f32_e32 v15, v15
	v_add_f32_e32 v174, v14, v174
	v_cvt_pk_bf16_f32 v0, v0, v1
	v_add_f32_e32 v174, v15, v174
	v_cvt_pk_bf16_f32 v1, v2, v3
	v_add_f32_e32 v191, v191, v174
	v_cvt_pk_bf16_f32 v2, v4, v5
	v_cvt_pk_bf16_f32 v3, v6, v7
	v_cvt_pk_bf16_f32 v4, v8, v9
	v_cvt_pk_bf16_f32 v5, v10, v11
	v_cvt_pk_bf16_f32 v6, v12, v13
	v_cvt_pk_bf16_f32 v7, v14, v15
	ds_read_b128 v[8:11], v173 offset:42048
	ds_read_b128 v[12:15], v173 offset:44608
	s_setprio 1
	s_waitcnt lgkmcnt(10)
	v_mfma_f32_16x16x32_bf16 v[106:109], v[122:125], v[146:149], v[106:109]
	v_mfma_f32_16x16x32_bf16 v[110:113], v[122:125], v[0:3], v[110:113]
	v_mfma_f32_16x16x32_bf16 v[98:101], v[126:129], v[146:149], v[98:101]
	v_mfma_f32_16x16x32_bf16 v[102:105], v[126:129], v[0:3], v[102:105]
	s_waitcnt lgkmcnt(8)
	v_mfma_f32_16x16x32_bf16 v[90:93], v[130:133], v[146:149], v[90:93]
	v_mfma_f32_16x16x32_bf16 v[94:97], v[130:133], v[0:3], v[94:97]
	v_mfma_f32_16x16x32_bf16 v[78:81], v[142:145], v[146:149], v[78:81]
	v_mfma_f32_16x16x32_bf16 v[74:77], v[142:145], v[0:3], v[74:77]
	ds_read_b128 v[122:125], v173 offset:47168
	ds_read_b128 v[126:129], v173 offset:49728
	ds_read_b128 v[130:133], v173 offset:52288
	ds_read_b128 v[142:145], v173 offset:54848
	s_waitcnt lgkmcnt(10)
	v_mfma_f32_16x16x32_bf16 v[62:65], v[16:19], v[146:149], v[62:65]
	v_mfma_f32_16x16x32_bf16 v[70:73], v[16:19], v[0:3], v[70:73]
	v_mfma_f32_16x16x32_bf16 v[50:53], v[20:23], v[146:149], v[50:53]
	v_mfma_f32_16x16x32_bf16 v[66:69], v[20:23], v[0:3], v[66:69]
	s_waitcnt lgkmcnt(8)
	v_mfma_f32_16x16x32_bf16 v[54:57], v[24:27], v[146:149], v[54:57]
	v_mfma_f32_16x16x32_bf16 v[58:61], v[24:27], v[0:3], v[58:61]
	v_mfma_f32_16x16x32_bf16 v[82:85], v[28:31], v[146:149], v[82:85]
	v_mfma_f32_16x16x32_bf16 v[86:89], v[28:31], v[0:3], v[86:89]
	s_waitcnt lgkmcnt(6)
	v_mfma_f32_16x16x32_bf16 v[106:109], v[154:157], v[150:153], v[106:109]
	v_mfma_f32_16x16x32_bf16 v[110:113], v[154:157], v[4:7], v[110:113]
	v_mfma_f32_16x16x32_bf16 v[98:101], v[158:161], v[150:153], v[98:101]
	v_mfma_f32_16x16x32_bf16 v[102:105], v[158:161], v[4:7], v[102:105]
	s_waitcnt lgkmcnt(4)
	v_mfma_f32_16x16x32_bf16 v[90:93], v[8:11], v[150:153], v[90:93]
	v_mfma_f32_16x16x32_bf16 v[94:97], v[8:11], v[4:7], v[94:97]
	v_mfma_f32_16x16x32_bf16 v[78:81], v[12:15], v[150:153], v[78:81]
	v_mfma_f32_16x16x32_bf16 v[74:77], v[12:15], v[4:7], v[74:77]
	s_waitcnt lgkmcnt(2)
	v_mfma_f32_16x16x32_bf16 v[62:65], v[122:125], v[150:153], v[62:65]
	v_mfma_f32_16x16x32_bf16 v[70:73], v[122:125], v[4:7], v[70:73]
	v_mfma_f32_16x16x32_bf16 v[50:53], v[126:129], v[150:153], v[50:53]
	v_mfma_f32_16x16x32_bf16 v[66:69], v[126:129], v[4:7], v[66:69]
	s_waitcnt lgkmcnt(0)
	v_mfma_f32_16x16x32_bf16 v[54:57], v[130:133], v[150:153], v[54:57]
	v_mfma_f32_16x16x32_bf16 v[58:61], v[130:133], v[4:7], v[58:61]
	v_mfma_f32_16x16x32_bf16 v[82:85], v[142:145], v[150:153], v[82:85]
	v_mfma_f32_16x16x32_bf16 v[86:89], v[142:145], v[4:7], v[86:89]
	s_setprio 0
	s_branch .LBB0_1784

; template <int NC, int DQK, int DV, bool CAUSAL, bool PF> ...
;     ...
;       _Pragma("unroll") for (int ks = 0; ks < NKS; ++ks) _Pragma("unroll") for (int m = 0; m < 4; ++m) {
;         bf16x8 a = *(const bf16x8*)&Kb[(16 * m + fr) * KLD + c * DQK + ks * 32 + fq * 8];
;         s[m] = __builtin_amdgcn_mfma_f32_16x16x32_bf16(a, qf[c][ks], s[m], 0, 0, 0);
;     ...
;     _Pragma("unroll") for (int k2 = 0; k2 < 2; ++k2) _Pragma("unroll") for (int v = 0; v < NVT; ++v) {
;       bf16x8 a = *(const bf16x8*)&Vb[(16 * v + fr) * VLD + 32 * k2 + fq * 8];
;       _Pragma("unroll") for (int c = 0; c < NC; ++c) O[c][v] = __builtin_amdgcn_mfma_f32_16x16x32_bf16(a, pf[c][k2], O[c][v], 0, 0, 0);
;       if ((v & 3) == 3) __builtin_amdgcn_sched_barrier(0);
;     }
.Ldb_fastB:
	s_setprio 1
	v_add3_u32 v172, s38, v32, v195
	s_cmp_eq_u32 s34, 0
	s_cbranch_scc1 .Ldb_B_nopend
	s_sub_i32 s8, s37, 0x5000
	s_cmp_lt_i32 s8, 0
	s_cselect_b32 s8, 0xa000, s8
	v_add3_u32 v173, s8, v32, v193
	ds_read_b128 v[0:3], v173 offset:36864
	ds_read_b128 v[4:7], v173 offset:39424
	ds_read_b128 v[8:11], v173 offset:41984
	ds_read_b128 v[12:15], v173 offset:44544
	ds_read_b128 v[16:19], v173 offset:47104
	ds_read_b128 v[20:23], v173 offset:49664
	ds_read_b128 v[24:27], v173 offset:52224
	ds_read_b128 v[28:31], v173 offset:54784
	ds_read_b128 v[122:125], v173 offset:36928
	ds_read_b128 v[126:129], v173 offset:39488
	ds_read_b128 v[130:133], v173 offset:42048
	ds_read_b128 v[142:145], v173 offset:44608
	s_waitcnt lgkmcnt(10)
	v_mfma_f32_16x16x32_bf16 v[106:109], v[0:3], v[146:149], v[106:109]
	v_mfma_f32_16x16x32_bf16 v[110:113], v[0:3], v[154:157], v[110:113]
	v_mfma_f32_16x16x32_bf16 v[98:101], v[4:7], v[146:149], v[98:101]
	v_mfma_f32_16x16x32_bf16 v[102:105], v[4:7], v[154:157], v[102:105]
	s_waitcnt lgkmcnt(8)
	v_mfma_f32_16x16x32_bf16 v[90:93], v[8:11], v[146:149], v[90:93]
	v_mfma_f32_16x16x32_bf16 v[94:97], v[8:11], v[154:157], v[94:97]
	v_mfma_f32_16x16x32_bf16 v[78:81], v[12:15], v[146:149], v[78:81]
	v_mfma_f32_16x16x32_bf16 v[74:77], v[12:15], v[154:157], v[74:77]
	ds_read_b128 v[0:3], v173 offset:47168
	ds_read_b128 v[4:7], v173 offset:49728
	ds_read_b128 v[8:11], v173 offset:52288
	ds_read_b128 v[12:15], v173 offset:54848
	s_waitcnt lgkmcnt(10)
	v_mfma_f32_16x16x32_bf16 v[62:65], v[16:19], v[146:149], v[62:65]
	v_mfma_f32_16x16x32_bf16 v[70:73], v[16:19], v[154:157], v[70:73]
	v_mfma_f32_16x16x32_bf16 v[50:53], v[20:23], v[146:149], v[50:53]
	v_mfma_f32_16x16x32_bf16 v[66:69], v[20:23], v[154:157], v[66:69]
	s_waitcnt lgkmcnt(8)
	v_mfma_f32_16x16x32_bf16 v[54:57], v[24:27], v[146:149], v[54:57]
	v_mfma_f32_16x16x32_bf16 v[58:61], v[24:27], v[154:157], v[58:61]
	v_mfma_f32_16x16x32_bf16 v[82:85], v[28:31], v[146:149], v[82:85]
	v_mfma_f32_16x16x32_bf16 v[86:89], v[28:31], v[154:157], v[86:89]
	ds_read_b128 v[16:19], v172 offset:64
	ds_read_b128 v[20:23], v172 offset:4672
	ds_read_b128 v[24:27], v172 offset:9280
	ds_read_b128 v[28:31], v172 offset:13888
	s_waitcnt lgkmcnt(10)
	v_mfma_f32_16x16x32_bf16 v[106:109], v[122:125], v[150:153], v[106:109]
	v_mfma_f32_16x16x32_bf16 v[110:113], v[122:125], v[158:161], v[110:113]
	v_mfma_f32_16x16x32_bf16 v[98:101], v[126:129], v[150:153], v[98:101]
	v_mfma_f32_16x16x32_bf16 v[102:105], v[126:129], v[158:161], v[102:105]
	s_waitcnt lgkmcnt(8)
	v_mfma_f32_16x16x32_bf16 v[90:93], v[130:133], v[150:153], v[90:93]
	v_mfma_f32_16x16x32_bf16 v[94:97], v[130:133], v[158:161], v[94:97]
	v_mfma_f32_16x16x32_bf16 v[78:81], v[142:145], v[150:153], v[78:81]
	v_mfma_f32_16x16x32_bf16 v[74:77], v[142:145], v[158:161], v[74:77]
	ds_read_b128 v[122:125], v172
	ds_read_b128 v[126:129], v172 offset:4608
	ds_read_b128 v[130:133], v172 offset:9216
	ds_read_b128 v[142:145], v172 offset:13824
	s_waitcnt lgkmcnt(10)
	v_mfma_f32_16x16x32_bf16 v[62:65], v[0:3], v[150:153], v[62:65]
	v_mfma_f32_16x16x32_bf16 v[70:73], v[0:3], v[158:161], v[70:73]
	v_mfma_f32_16x16x32_bf16 v[50:53], v[4:7], v[150:153], v[50:53]
	v_mfma_f32_16x16x32_bf16 v[66:69], v[4:7], v[158:161], v[66:69]
	s_waitcnt lgkmcnt(8)
	v_mfma_f32_16x16x32_bf16 v[54:57], v[8:11], v[150:153], v[54:57]
	v_mfma_f32_16x16x32_bf16 v[58:61], v[8:11], v[158:161], v[58:61]
	v_mfma_f32_16x16x32_bf16 v[82:85], v[12:15], v[150:153], v[82:85]
	v_mfma_f32_16x16x32_bf16 v[86:89], v[12:15], v[158:161], v[86:89]
	ds_read_b128 v[0:3], v172 offset:128
	ds_read_b128 v[4:7], v172 offset:4736
	ds_read_b128 v[8:11], v172 offset:9344
	ds_read_b128 v[12:15], v172 offset:13952
	s_branch .Ldb_B_qk

; template <int NC, int DQK, int DV, bool CAUSAL, bool PF> ...
;     ...
;       _Pragma("unroll") for (int ks = 0; ks < NKS; ++ks) _Pragma("unroll") for (int m = 0; m < 4; ++m) {
;         bf16x8 a = *(const bf16x8*)&Kb[(16 * m + fr) * KLD + c * DQK + ks * 32 + fq * 8];
;         s[m] = __builtin_amdgcn_mfma_f32_16x16x32_bf16(a, qf[c][ks], s[m], 0, 0, 0);
;       }
;       constexpr float THR = 8.f;
;       float tnew, psum = 0.f;
;       if (general) {
;         float tmax = -1e30f;
;         _Pragma("unroll") for (int m = 0; m < 4; ++m) _Pragma("unroll") for (int j = 0; j < 4; ++j) {
;           float v = s[m][j] * scale_log2 + bv[m][j];
;           s[m][j] = v; tmax = fmaxf(tmax, v);
;         }
;         tnew = tmax;
;       } else {
;         float rmax = fmaxf(fmaxf(s[0][0], s[0][1]), fmaxf(s[0][2], s[0][3]));
;         _Pragma("unroll") for (int m = 1; m < 4; ++m) rmax = fmaxf(rmax, fmaxf(fmaxf(s[m][0], s[m][1]), fmaxf(s[m][2], s[m][3])));
;         tnew = rmax * scale_log2 + bb;
;       }
;       if (__builtin_amdgcn_ballot_w64(tnew - mrun[c] > THR) != 0ull) {
.Ldb_B_qk:
	s_waitcnt lgkmcnt(4)
	v_mfma_f32_16x16x32_bf16 v[122:125], v[122:125], v[138:141], 0
	v_mfma_f32_16x16x32_bf16 v[126:129], v[126:129], v[138:141], 0
	v_mfma_f32_16x16x32_bf16 v[130:133], v[130:133], v[138:141], 0
	v_mfma_f32_16x16x32_bf16 v[142:145], v[142:145], v[138:141], 0
	v_mfma_f32_16x16x32_bf16 v[122:125], v[16:19], v[134:137], v[122:125]
	v_mfma_f32_16x16x32_bf16 v[126:129], v[20:23], v[134:137], v[126:129]
	v_mfma_f32_16x16x32_bf16 v[130:133], v[24:27], v[134:137], v[130:133]
	v_mfma_f32_16x16x32_bf16 v[142:145], v[28:31], v[134:137], v[142:145]
	ds_read_b128 v[16:19], v172 offset:192
	ds_read_b128 v[20:23], v172 offset:4800
	ds_read_b128 v[24:27], v172 offset:9408
	ds_read_b128 v[28:31], v172 offset:14016
	s_waitcnt lgkmcnt(4)
	v_mfma_f32_16x16x32_bf16 v[0:3], v[0:3], v[118:121], 0
	v_mfma_f32_16x16x32_bf16 v[4:7], v[4:7], v[118:121], 0
	v_mfma_f32_16x16x32_bf16 v[8:11], v[8:11], v[118:121], 0
	v_mfma_f32_16x16x32_bf16 v[12:15], v[12:15], v[118:121], 0
	s_setprio 0
	v_max3_f32 v174, v122, v123, v124
	v_max3_f32 v175, v125, v126, v127
	v_max3_f32 v174, v174, v128, v129
	v_max3_f32 v175, v175, v130, v131
	v_max3_f32 v174, v174, v132, v133
	v_max3_f32 v175, v175, v142, v143
	v_max3_f32 v174, v174, v144, v145
	v_max_f32_e32 v174, v174, v175
	v_fmamk_f32 v174, v174, 0x3e38aa3b, v170
	v_sub_f32_e32 v175, v174, v194
	v_cmp_lt_f32_e32 vcc, s33, v175
	s_cbranch_vccnz .Ldb_resc0
